# static priority for waves 4-7 re-applied at every phase entry (prologue, prefix, final norm and GEMM prologues too)
# speedup vs baseline: 1.0105x; 1.0057x over previous
; __global__ void __launch_bounds__(NTHREADS, 2) fwd_kernel(Args a) {
;     ...
;     for (int ph = a.ph_lo; ph < a.ph_hi; ++ph) {
;         unsigned char* ws = a.ws; asm volatile("" : "+s"(ws));
;         bf16_t* xb = (bf16_t*)(ws + WS_XB); bf16_t* r1 = (bf16_t*)(ws + WS_R1); bf16_t* yb = (bf16_t*)(ws + WS_Y); float* ssq = (float*)(ws + WS_SSQ);
;         int tid; asm volatile("v_mbcnt_lo_u32_b32 %0, -1, 0\n\tv_mbcnt_hi_u32_b32 %0, -1, %0" : "=v"(tid)); tid += wave_s * 64;
.LBB0_11:
	s_mov_b64 s[78:79], s[66:67]
	v_mbcnt_lo_u32_b32 v221, -1, 0
	v_mbcnt_hi_u32_b32 v221, -1, v221
	s_waitcnt lgkmcnt(0)
	s_mov_b64 s[8:9], -1
	v_add_u32_e32 v220, s89, v221
	s_setprio 0
	s_cmp_lt_u32 s89, 0x100
	s_cbranch_scc1 .Lprio_ph_done
	s_setprio 1
.Lprio_ph_done:
	s_mov_b64 s[4:5], 0
	s_cmp_lt_i32 s82, 15
	s_mov_b64 s[6:7], 0
	s_cbranch_scc0 .LBB0_16
	s_and_b64 vcc, exec, s[8:9]
	s_cbranch_vccnz .LBB0_22
